# fallback-mode seam paths get their own vmcnt(0)+s_barrier back (LDS ring hand-off to the hook stays ordered when the grid-barrier path is taken)
# speedup vs baseline: 1.0141x; 1.0034x over previous
.LBB0_1014:
	s_waitcnt vmcnt(0)
	s_barrier
	s_cbranch_execnz .LBB0_1020
	s_branch .LBB0_1076
